# EpiResid pipelined epilogue reordered so both 64B halves of each 128B line are loaded/stored back-to-back
# speedup vs baseline: 1.0014x; 1.0014x over previous
;     __device__ __forceinline__ void operator()(const f32x4 (&acc)[2][2][4][2], const Unit& u, int wr, int wc, int fr_, int fq_) const {
;     ...
;         const int pm = u.pm + pm_off; const float* bs; float* o;
;         if (pm < G_NTL) { bs = base_l + (size_t)pm * 256 * G_D; o = out_l + (size_t)pm * 256 * G_D; } else { bs = base_c + (size_t)(pm - G_NTL) * 256 * G_D; o = out_c + (size_t)(pm - G_NTL) * 256 * G_D; }
;         const float* gt = gate + (size_t)tile_modrow(pm) * G_MODW;
;         const int col0 = u.pn * BM + wc * 32 + 4 * fq;
; #pragma unroll
;         for (int bj = 0; bj < 2; ++bj)
; #pragma unroll
;             for (int n = 0; n < 2; ++n) { const int c = col0 + bj * HALF + n * 16; const f32x4 gv = *(const f32x4*)(gt + c);
; #pragma unroll
;                 for (int ai = 0; ai < 2; ++ai)
; #pragma unroll
;                     for (int m = 0; m < 4; ++m) { const size_t off = (size_t)(ai * HALF + wr * 64 + m * 16 + fr) * G_D + c; *(f32x4*)(o + off) = *(const f32x4*)(bs + off) + gv * acc[ai][bj][m][n]; } }
.LBB0_1645:
	s_add_i32 s70, s70, s61
	s_add_i32 s26, s70, 0xffffff80
	s_ashr_i32 s27, s70, 31
	s_cmpk_lt_i32 s70, 0x80
	s_cselect_b32 s27, s27, 0
	s_cselect_b32 s26, s70, s26
	s_cselect_b32 s29, s19, s21
	s_cselect_b32 s28, s18, s20
	s_cselect_b32 s72, s13, s58
	s_cselect_b32 s73, s12, s57
	s_lshl_b64 s[26:27], s[26:27], 20
	s_add_u32 s28, s28, s26
	s_addc_u32 s29, s29, s27
	s_add_u32 s26, s73, s26
	s_addc_u32 s27, s72, s27
	s_min_i32 s70, s70, 0x80
	s_ashr_i32 s70, s70, 3
	s_mul_hi_i32 s73, s70, 0x6000
	s_mulk_i32 s70, 0x6000
	s_add_u32 s72, s59, s70
	v_mov_b32_e32 v128, v147
	v_mov_b32_e32 v129, v146
	s_addc_u32 s73, s60, s73
	s_lshl_b32 s70, s71, 8
	s_or_b32 s70, s70, s66
	v_add_u32_e32 v144, s65, v128
	v_lshl_add_u32 v142, v129, 2, s70
	v_lshlrev_b32_e32 v145, 12, v144
	v_lshlrev_b32_e32 v143, 2, v142
	v_lshl_add_u32 v150, v142, 2, v145
	global_load_dwordx4 v[128:131], v143, s[72:73]
	global_load_dwordx4 v[138:141], v143, s[72:73] offset:64
	global_load_dwordx4 v[158:161], v143, s[72:73] offset:512
	global_load_dwordx4 v[162:165], v143, s[72:73] offset:576
	v_add_u32_e32 v151, 0x10000, v150
	v_add_u32_e32 v152, 0x20000, v150
	v_add_u32_e32 v153, 0x30000, v150
	v_add_u32_e32 v154, 0x80000, v150
	v_add_u32_e32 v155, 0x90000, v150
	v_add_u32_e32 v156, 0xa0000, v150
	v_add_u32_e32 v157, 0xb0000, v150
	global_load_dwordx4 v[166:169], v150, s[28:29]
	global_load_dwordx4 v[170:173], v150, s[28:29] offset:64
	global_load_dwordx4 v[174:177], v151, s[28:29]
	global_load_dwordx4 v[178:181], v151, s[28:29] offset:64
	global_load_dwordx4 v[182:185], v152, s[28:29]
	global_load_dwordx4 v[192:195], v152, s[28:29] offset:64
	global_load_dwordx4 v[230:233], v153, s[28:29]
	global_load_dwordx4 v[234:237], v153, s[28:29] offset:64
	s_and_b64 vcc, exec, s[6:7]
	s_waitcnt vmcnt(7)
	v_pk_fma_f32 v[126:127], v[126:127], v[130:131], v[168:169]
	v_pk_fma_f32 v[124:125], v[124:125], v[128:129], v[166:167]
	global_load_dwordx4 v[166:169], v154, s[28:29]
	global_store_dwordx4 v150, v[124:127], s[26:27]
	s_waitcnt vmcnt(8)
	v_pk_fma_f32 v[98:99], v[98:99], v[140:141], v[172:173]
	v_pk_fma_f32 v[96:97], v[96:97], v[138:139], v[170:171]
	global_load_dwordx4 v[170:173], v154, s[28:29] offset:64
	global_store_dwordx4 v150, v[96:99], s[26:27] offset:64
	s_waitcnt vmcnt(9)
	v_pk_fma_f32 v[122:123], v[122:123], v[130:131], v[176:177]
	v_pk_fma_f32 v[120:121], v[120:121], v[128:129], v[174:175]
	global_load_dwordx4 v[174:177], v155, s[28:29]
	global_store_dwordx4 v151, v[120:123], s[26:27]
	s_waitcnt vmcnt(10)
	v_pk_fma_f32 v[94:95], v[94:95], v[140:141], v[180:181]
	v_pk_fma_f32 v[92:93], v[92:93], v[138:139], v[178:179]
	global_load_dwordx4 v[178:181], v155, s[28:29] offset:64
	global_store_dwordx4 v151, v[92:95], s[26:27] offset:64
	s_waitcnt vmcnt(11)
	v_pk_fma_f32 v[118:119], v[118:119], v[130:131], v[184:185]
	v_pk_fma_f32 v[116:117], v[116:117], v[128:129], v[182:183]
	global_load_dwordx4 v[182:185], v156, s[28:29]
	global_store_dwordx4 v152, v[116:119], s[26:27]
	s_waitcnt vmcnt(12)
	v_pk_fma_f32 v[90:91], v[90:91], v[140:141], v[194:195]
	v_pk_fma_f32 v[88:89], v[88:89], v[138:139], v[192:193]
	global_load_dwordx4 v[192:195], v156, s[28:29] offset:64
	global_store_dwordx4 v152, v[88:91], s[26:27] offset:64
	s_waitcnt vmcnt(13)
	v_pk_fma_f32 v[114:115], v[114:115], v[130:131], v[232:233]
	v_pk_fma_f32 v[112:113], v[112:113], v[128:129], v[230:231]
	global_load_dwordx4 v[230:233], v157, s[28:29]
	global_store_dwordx4 v153, v[112:115], s[26:27]
	s_waitcnt vmcnt(14)
	v_pk_fma_f32 v[82:83], v[82:83], v[140:141], v[236:237]
	v_pk_fma_f32 v[80:81], v[80:81], v[138:139], v[234:235]
	global_load_dwordx4 v[234:237], v157, s[28:29] offset:64
	global_store_dwordx4 v153, v[80:83], s[26:27] offset:64
	s_waitcnt vmcnt(15)
	v_pk_fma_f32 v[110:111], v[110:111], v[130:131], v[168:169]
	v_pk_fma_f32 v[108:109], v[108:109], v[128:129], v[166:167]
	global_load_dwordx4 v[166:169], v150, s[28:29] offset:512
	global_store_dwordx4 v154, v[108:111], s[26:27]
	s_waitcnt vmcnt(15)
	v_pk_fma_f32 v[78:79], v[78:79], v[140:141], v[172:173]
	v_pk_fma_f32 v[76:77], v[76:77], v[138:139], v[170:171]
	global_load_dwordx4 v[170:173], v150, s[28:29] offset:576
	global_store_dwordx4 v154, v[76:79], s[26:27] offset:64
	s_waitcnt vmcnt(15)
	v_pk_fma_f32 v[106:107], v[106:107], v[130:131], v[176:177]
	v_pk_fma_f32 v[104:105], v[104:105], v[128:129], v[174:175]
	global_load_dwordx4 v[174:177], v151, s[28:29] offset:512
	global_store_dwordx4 v155, v[104:107], s[26:27]
	s_waitcnt vmcnt(15)
	v_pk_fma_f32 v[70:71], v[70:71], v[140:141], v[180:181]
	v_pk_fma_f32 v[68:69], v[68:69], v[138:139], v[178:179]
	global_load_dwordx4 v[178:181], v151, s[28:29] offset:576
	global_store_dwordx4 v155, v[68:71], s[26:27] offset:64
	s_waitcnt vmcnt(15)
;     __device__ __forceinline__ void operator()(const f32x4 (&acc)[2][2][4][2], const Unit& u, int wr, int wc, int fr_, int fq_) const {
;     ...
;             for (int n = 0; n < 2; ++n) { const int c = col0 + bj * HALF + n * 16; const f32x4 gv = *(const f32x4*)(gt + c);
; #pragma unroll
;                 for (int ai = 0; ai < 2; ++ai)
; #pragma unroll
;                     for (int m = 0; m < 4; ++m) { const size_t off = (size_t)(ai * HALF + wr * 64 + m * 16 + fr) * G_D + c; *(f32x4*)(o + off) = *(const f32x4*)(bs + off) + gv * acc[ai][bj][m][n]; } }
	v_pk_fma_f32 v[102:103], v[102:103], v[130:131], v[184:185]
	v_pk_fma_f32 v[100:101], v[100:101], v[128:129], v[182:183]
	global_load_dwordx4 v[182:185], v152, s[28:29] offset:512
	global_store_dwordx4 v156, v[100:103], s[26:27]
	s_waitcnt vmcnt(15)
	v_pk_fma_f32 v[62:63], v[62:63], v[140:141], v[194:195]
	v_pk_fma_f32 v[60:61], v[60:61], v[138:139], v[192:193]
	global_load_dwordx4 v[192:195], v152, s[28:29] offset:576
	global_store_dwordx4 v156, v[60:63], s[26:27] offset:64
	s_waitcnt vmcnt(15)
	v_pk_fma_f32 v[86:87], v[86:87], v[130:131], v[232:233]
	v_pk_fma_f32 v[84:85], v[84:85], v[128:129], v[230:231]
	global_load_dwordx4 v[230:233], v153, s[28:29] offset:512
	global_store_dwordx4 v157, v[84:87], s[26:27]
	s_waitcnt vmcnt(15)
	v_pk_fma_f32 v[54:55], v[54:55], v[140:141], v[236:237]
	v_pk_fma_f32 v[52:53], v[52:53], v[138:139], v[234:235]
	global_load_dwordx4 v[234:237], v153, s[28:29] offset:576
	global_store_dwordx4 v157, v[52:55], s[26:27] offset:64
	s_waitcnt vmcnt(15)
	v_pk_fma_f32 v[74:75], v[74:75], v[160:161], v[168:169]
	v_pk_fma_f32 v[72:73], v[72:73], v[158:159], v[166:167]
	global_load_dwordx4 v[166:169], v154, s[28:29] offset:512
	global_store_dwordx4 v150, v[72:75], s[26:27] offset:512
	s_waitcnt vmcnt(15)
	v_pk_fma_f32 v[46:47], v[46:47], v[164:165], v[172:173]
	v_pk_fma_f32 v[44:45], v[44:45], v[162:163], v[170:171]
	global_load_dwordx4 v[170:173], v154, s[28:29] offset:576
	global_store_dwordx4 v150, v[44:47], s[26:27] offset:576
	s_waitcnt vmcnt(15)
	v_pk_fma_f32 v[66:67], v[66:67], v[160:161], v[176:177]
	v_pk_fma_f32 v[64:65], v[64:65], v[158:159], v[174:175]
	global_load_dwordx4 v[174:177], v155, s[28:29] offset:512
	global_store_dwordx4 v151, v[64:67], s[26:27] offset:512
	s_waitcnt vmcnt(15)
	v_pk_fma_f32 v[38:39], v[38:39], v[164:165], v[180:181]
	v_pk_fma_f32 v[36:37], v[36:37], v[162:163], v[178:179]
	global_load_dwordx4 v[178:181], v155, s[28:29] offset:576
	global_store_dwordx4 v151, v[36:39], s[26:27] offset:576
	s_waitcnt vmcnt(15)
	v_pk_fma_f32 v[58:59], v[58:59], v[160:161], v[184:185]
	v_pk_fma_f32 v[56:57], v[56:57], v[158:159], v[182:183]
	global_load_dwordx4 v[182:185], v156, s[28:29] offset:512
	global_store_dwordx4 v152, v[56:59], s[26:27] offset:512
	s_waitcnt vmcnt(15)
	v_pk_fma_f32 v[30:31], v[30:31], v[164:165], v[194:195]
	v_pk_fma_f32 v[28:29], v[28:29], v[162:163], v[192:193]
	global_load_dwordx4 v[192:195], v156, s[28:29] offset:576
	global_store_dwordx4 v152, v[28:31], s[26:27] offset:576
	s_waitcnt vmcnt(15)
	v_pk_fma_f32 v[50:51], v[50:51], v[160:161], v[232:233]
	v_pk_fma_f32 v[48:49], v[48:49], v[158:159], v[230:231]
	global_load_dwordx4 v[230:233], v157, s[28:29] offset:512
	global_store_dwordx4 v153, v[48:51], s[26:27] offset:512
	s_waitcnt vmcnt(15)
	v_pk_fma_f32 v[22:23], v[22:23], v[164:165], v[236:237]
	v_pk_fma_f32 v[20:21], v[20:21], v[162:163], v[234:235]
	global_load_dwordx4 v[234:237], v157, s[28:29] offset:576
	global_store_dwordx4 v153, v[20:23], s[26:27] offset:576
	s_waitcnt vmcnt(15)
	v_pk_fma_f32 v[42:43], v[42:43], v[160:161], v[168:169]
	v_pk_fma_f32 v[40:41], v[40:41], v[158:159], v[166:167]
	global_store_dwordx4 v154, v[40:43], s[26:27] offset:512
	s_waitcnt vmcnt(14)
	v_pk_fma_f32 v[14:15], v[14:15], v[164:165], v[172:173]
	v_pk_fma_f32 v[12:13], v[12:13], v[162:163], v[170:171]
	global_store_dwordx4 v154, v[12:15], s[26:27] offset:576
	s_waitcnt vmcnt(13)
	v_pk_fma_f32 v[34:35], v[34:35], v[160:161], v[176:177]
	v_pk_fma_f32 v[32:33], v[32:33], v[158:159], v[174:175]
	global_store_dwordx4 v155, v[32:35], s[26:27] offset:512
	s_waitcnt vmcnt(12)
	v_pk_fma_f32 v[10:11], v[10:11], v[164:165], v[180:181]
	v_pk_fma_f32 v[8:9], v[8:9], v[162:163], v[178:179]
	global_store_dwordx4 v155, v[8:11], s[26:27] offset:576
	s_waitcnt vmcnt(11)
	v_pk_fma_f32 v[26:27], v[26:27], v[160:161], v[184:185]
	v_pk_fma_f32 v[24:25], v[24:25], v[158:159], v[182:183]
	global_store_dwordx4 v156, v[24:27], s[26:27] offset:512
	s_waitcnt vmcnt(10)
	v_pk_fma_f32 v[6:7], v[6:7], v[164:165], v[194:195]
	v_pk_fma_f32 v[4:5], v[4:5], v[162:163], v[192:193]
	global_store_dwordx4 v156, v[4:7], s[26:27] offset:576
	s_waitcnt vmcnt(9)
	v_pk_fma_f32 v[18:19], v[18:19], v[160:161], v[232:233]
	v_pk_fma_f32 v[16:17], v[16:17], v[158:159], v[230:231]
	global_store_dwordx4 v157, v[16:19], s[26:27] offset:512
	s_waitcnt vmcnt(8)
	v_pk_fma_f32 v[2:3], v[2:3], v[164:165], v[236:237]
	v_pk_fma_f32 v[0:1], v[0:1], v[162:163], v[234:235]
	global_store_dwordx4 v157, v[0:3], s[26:27] offset:576
	s_mov_b64 s[26:27], -1
	s_cbranch_vccnz .LBB0_1630
	s_andn2_b64 vcc, exec, s[22:23]
	s_cbranch_vccnz .LBB0_1629
	s_barrier
	s_branch .LBB0_1629

;     __device__ __forceinline__ void operator()(const f32x4 (&acc)[2][2][4][2], const Unit& u, int wr, int wc, int fr_, int fq_) const {
;     ...
;         const int pm = u.pm + pm_off; const float* bs; float* o;
;         if (pm < G_NTL) { bs = base_l + (size_t)pm * 256 * G_D; o = out_l + (size_t)pm * 256 * G_D; } else { bs = base_c + (size_t)(pm - G_NTL) * 256 * G_D; o = out_c + (size_t)(pm - G_NTL) * 256 * G_D; }
;         const float* gt = gate + (size_t)tile_modrow(pm) * G_MODW;
;         const int col0 = u.pn * BM + wc * 32 + 4 * fq;
; #pragma unroll
;         for (int bj = 0; bj < 2; ++bj)
; #pragma unroll
;             for (int n = 0; n < 2; ++n) { const int c = col0 + bj * HALF + n * 16; const f32x4 gv = *(const f32x4*)(gt + c);
; #pragma unroll
;                 for (int ai = 0; ai < 2; ++ai)
; #pragma unroll
;                     for (int m = 0; m < 4; ++m) { const size_t off = (size_t)(ai * HALF + wr * 64 + m * 16 + fr) * G_D + c; *(f32x4*)(o + off) = *(const f32x4*)(bs + off) + gv * acc[ai][bj][m][n]; } }
.LBB0_1996:
	s_add_i32 s24, s63, s54
	s_add_i32 s22, s24, 0xffffff80
	s_ashr_i32 s23, s24, 31
	s_cmpk_lt_i32 s24, 0x80
	s_cselect_b32 s23, s23, 0
	s_cselect_b32 s22, s24, s22
	s_cselect_b32 s25, s13, s51
	s_cselect_b32 s26, s12, s50
	s_lshl_b64 s[22:23], s[22:23], 20
	s_add_u32 s22, s26, s22
	s_addc_u32 s23, s25, s23
	s_min_i32 s24, s24, 0x80
	s_ashr_i32 s24, s24, 3
	s_mul_hi_i32 s25, s24, 0x6000
	s_mulk_i32 s24, 0x6000
	s_add_u32 s24, s52, s24
	v_mov_b32_e32 v135, v139
	v_mov_b32_e32 v134, v138
	s_addc_u32 s25, s53, s25
	s_lshl_b32 s26, s64, 8
	s_or_b32 s26, s26, s56
	v_lshl_add_u32 v134, v134, 2, s26
	v_add_u32_e32 v150, s55, v135
	v_lshlrev_b32_e32 v136, 12, v150
	v_lshlrev_b32_e32 v135, 2, v134
	v_lshl_add_u32 v142, v134, 2, v136
	global_load_dwordx4 v[152:155], v135, s[24:25]
	global_load_dwordx4 v[156:159], v135, s[24:25] offset:64
	global_load_dwordx4 v[160:163], v135, s[24:25] offset:512
	global_load_dwordx4 v[164:167], v135, s[24:25] offset:576
	v_add_u32_e32 v143, 0x10000, v142
	v_add_u32_e32 v144, 0x20000, v142
	v_add_u32_e32 v145, 0x30000, v142
	v_add_u32_e32 v146, 0x80000, v142
	v_add_u32_e32 v147, 0x90000, v142
	v_add_u32_e32 v148, 0xa0000, v142
	v_add_u32_e32 v149, 0xb0000, v142
	global_load_dwordx4 v[170:173], v142, s[22:23]
	global_load_dwordx4 v[174:177], v142, s[22:23] offset:64
	global_load_dwordx4 v[178:181], v143, s[22:23]
	global_load_dwordx4 v[182:185], v143, s[22:23] offset:64
	global_load_dwordx4 v[192:195], v144, s[22:23]
	global_load_dwordx4 v[230:233], v144, s[22:23] offset:64
	global_load_dwordx4 v[234:237], v145, s[22:23]
	global_load_dwordx4 v[238:241], v145, s[22:23] offset:64
	s_and_b64 vcc, exec, s[6:7]
	s_waitcnt vmcnt(7)
	v_pk_fma_f32 v[126:127], v[126:127], v[154:155], v[172:173]
	v_pk_fma_f32 v[124:125], v[124:125], v[152:153], v[170:171]
	global_load_dwordx4 v[170:173], v146, s[22:23]
	global_store_dwordx4 v142, v[124:127], s[22:23]
	s_waitcnt vmcnt(8)
	v_pk_fma_f32 v[98:99], v[98:99], v[158:159], v[176:177]
	v_pk_fma_f32 v[96:97], v[96:97], v[156:157], v[174:175]
	global_load_dwordx4 v[174:177], v146, s[22:23] offset:64
	global_store_dwordx4 v142, v[96:99], s[22:23] offset:64
	s_waitcnt vmcnt(9)
	v_pk_fma_f32 v[122:123], v[122:123], v[154:155], v[180:181]
	v_pk_fma_f32 v[120:121], v[120:121], v[152:153], v[178:179]
	global_load_dwordx4 v[178:181], v147, s[22:23]
	global_store_dwordx4 v143, v[120:123], s[22:23]
	s_waitcnt vmcnt(10)
	v_pk_fma_f32 v[94:95], v[94:95], v[158:159], v[184:185]
	v_pk_fma_f32 v[92:93], v[92:93], v[156:157], v[182:183]
	global_load_dwordx4 v[182:185], v147, s[22:23] offset:64
	global_store_dwordx4 v143, v[92:95], s[22:23] offset:64
	s_waitcnt vmcnt(11)
	v_pk_fma_f32 v[118:119], v[118:119], v[154:155], v[194:195]
	v_pk_fma_f32 v[116:117], v[116:117], v[152:153], v[192:193]
	global_load_dwordx4 v[192:195], v148, s[22:23]
	global_store_dwordx4 v144, v[116:119], s[22:23]
	s_waitcnt vmcnt(12)
	v_pk_fma_f32 v[86:87], v[86:87], v[158:159], v[232:233]
	v_pk_fma_f32 v[84:85], v[84:85], v[156:157], v[230:231]
	global_load_dwordx4 v[230:233], v148, s[22:23] offset:64
	global_store_dwordx4 v144, v[84:87], s[22:23] offset:64
	s_waitcnt vmcnt(13)
	v_pk_fma_f32 v[114:115], v[114:115], v[154:155], v[236:237]
	v_pk_fma_f32 v[112:113], v[112:113], v[152:153], v[234:235]
	global_load_dwordx4 v[234:237], v149, s[22:23]
	global_store_dwordx4 v145, v[112:115], s[22:23]
	s_waitcnt vmcnt(14)
	v_pk_fma_f32 v[82:83], v[82:83], v[158:159], v[240:241]
	v_pk_fma_f32 v[80:81], v[80:81], v[156:157], v[238:239]
	global_load_dwordx4 v[238:241], v149, s[22:23] offset:64
	global_store_dwordx4 v145, v[80:83], s[22:23] offset:64
	s_waitcnt vmcnt(15)
	v_pk_fma_f32 v[110:111], v[110:111], v[154:155], v[172:173]
	v_pk_fma_f32 v[108:109], v[108:109], v[152:153], v[170:171]
	global_load_dwordx4 v[170:173], v142, s[22:23] offset:512
	global_store_dwordx4 v146, v[108:111], s[22:23]
	s_waitcnt vmcnt(15)
	v_pk_fma_f32 v[78:79], v[78:79], v[158:159], v[176:177]
	v_pk_fma_f32 v[76:77], v[76:77], v[156:157], v[174:175]
	global_load_dwordx4 v[174:177], v142, s[22:23] offset:576
	global_store_dwordx4 v146, v[76:79], s[22:23] offset:64
	s_waitcnt vmcnt(15)
	v_pk_fma_f32 v[106:107], v[106:107], v[154:155], v[180:181]
	v_pk_fma_f32 v[104:105], v[104:105], v[152:153], v[178:179]
	global_load_dwordx4 v[178:181], v143, s[22:23] offset:512
	global_store_dwordx4 v147, v[104:107], s[22:23]
	s_waitcnt vmcnt(15)
	v_pk_fma_f32 v[74:75], v[74:75], v[158:159], v[184:185]
	v_pk_fma_f32 v[72:73], v[72:73], v[156:157], v[182:183]
	global_load_dwordx4 v[182:185], v143, s[22:23] offset:576
	global_store_dwordx4 v147, v[72:75], s[22:23] offset:64
	s_waitcnt vmcnt(15)
;     __device__ __forceinline__ void operator()(const f32x4 (&acc)[2][2][4][2], const Unit& u, int wr, int wc, int fr_, int fq_) const {
;     ...
;             for (int n = 0; n < 2; ++n) { const int c = col0 + bj * HALF + n * 16; const f32x4 gv = *(const f32x4*)(gt + c);
; #pragma unroll
;                 for (int ai = 0; ai < 2; ++ai)
; #pragma unroll
;                     for (int m = 0; m < 4; ++m) { const size_t off = (size_t)(ai * HALF + wr * 64 + m * 16 + fr) * G_D + c; *(f32x4*)(o + off) = *(const f32x4*)(bs + off) + gv * acc[ai][bj][m][n]; } }
	v_pk_fma_f32 v[102:103], v[102:103], v[154:155], v[194:195]
	v_pk_fma_f32 v[100:101], v[100:101], v[152:153], v[192:193]
	global_load_dwordx4 v[192:195], v144, s[22:23] offset:512
	global_store_dwordx4 v148, v[100:103], s[22:23]
	s_waitcnt vmcnt(15)
	v_pk_fma_f32 v[70:71], v[70:71], v[158:159], v[232:233]
	v_pk_fma_f32 v[68:69], v[68:69], v[156:157], v[230:231]
	global_load_dwordx4 v[230:233], v144, s[22:23] offset:576
	global_store_dwordx4 v148, v[68:71], s[22:23] offset:64
	s_waitcnt vmcnt(15)
	v_pk_fma_f32 v[90:91], v[90:91], v[154:155], v[236:237]
	v_pk_fma_f32 v[88:89], v[88:89], v[152:153], v[234:235]
	global_load_dwordx4 v[234:237], v145, s[22:23] offset:512
	global_store_dwordx4 v149, v[88:91], s[22:23]
	s_waitcnt vmcnt(15)
	v_pk_fma_f32 v[62:63], v[62:63], v[158:159], v[240:241]
	v_pk_fma_f32 v[60:61], v[60:61], v[156:157], v[238:239]
	global_load_dwordx4 v[238:241], v145, s[22:23] offset:576
	global_store_dwordx4 v149, v[60:63], s[22:23] offset:64
	s_waitcnt vmcnt(15)
	v_pk_fma_f32 v[66:67], v[66:67], v[162:163], v[172:173]
	v_pk_fma_f32 v[64:65], v[64:65], v[160:161], v[170:171]
	global_load_dwordx4 v[170:173], v146, s[22:23] offset:512
	global_store_dwordx4 v142, v[64:67], s[22:23] offset:512
	s_waitcnt vmcnt(15)
	v_pk_fma_f32 v[38:39], v[38:39], v[166:167], v[176:177]
	v_pk_fma_f32 v[36:37], v[36:37], v[164:165], v[174:175]
	global_load_dwordx4 v[174:177], v146, s[22:23] offset:576
	global_store_dwordx4 v142, v[36:39], s[22:23] offset:576
	s_waitcnt vmcnt(15)
	v_pk_fma_f32 v[58:59], v[58:59], v[162:163], v[180:181]
	v_pk_fma_f32 v[56:57], v[56:57], v[160:161], v[178:179]
	global_load_dwordx4 v[178:181], v147, s[22:23] offset:512
	global_store_dwordx4 v143, v[56:59], s[22:23] offset:512
	s_waitcnt vmcnt(15)
	v_pk_fma_f32 v[26:27], v[26:27], v[166:167], v[184:185]
	v_pk_fma_f32 v[24:25], v[24:25], v[164:165], v[182:183]
	global_load_dwordx4 v[182:185], v147, s[22:23] offset:576
	global_store_dwordx4 v143, v[24:27], s[22:23] offset:576
	s_waitcnt vmcnt(15)
	v_pk_fma_f32 v[54:55], v[54:55], v[162:163], v[194:195]
	v_pk_fma_f32 v[52:53], v[52:53], v[160:161], v[192:193]
	global_load_dwordx4 v[192:195], v148, s[22:23] offset:512
	global_store_dwordx4 v144, v[52:55], s[22:23] offset:512
	s_waitcnt vmcnt(15)
	v_pk_fma_f32 v[22:23], v[22:23], v[166:167], v[232:233]
	v_pk_fma_f32 v[20:21], v[20:21], v[164:165], v[230:231]
	global_load_dwordx4 v[230:233], v148, s[22:23] offset:576
	global_store_dwordx4 v144, v[20:23], s[22:23] offset:576
	s_waitcnt vmcnt(15)
	v_pk_fma_f32 v[50:51], v[50:51], v[162:163], v[236:237]
	v_pk_fma_f32 v[48:49], v[48:49], v[160:161], v[234:235]
	global_load_dwordx4 v[234:237], v149, s[22:23] offset:512
	global_store_dwordx4 v145, v[48:51], s[22:23] offset:512
	s_waitcnt vmcnt(15)
	v_pk_fma_f32 v[18:19], v[18:19], v[166:167], v[240:241]
	v_pk_fma_f32 v[16:17], v[16:17], v[164:165], v[238:239]
	global_load_dwordx4 v[238:241], v149, s[22:23] offset:576
	global_store_dwordx4 v145, v[16:19], s[22:23] offset:576
	s_waitcnt vmcnt(15)
	v_pk_fma_f32 v[46:47], v[46:47], v[162:163], v[172:173]
	v_pk_fma_f32 v[44:45], v[44:45], v[160:161], v[170:171]
	global_store_dwordx4 v146, v[44:47], s[22:23] offset:512
	s_waitcnt vmcnt(14)
	v_pk_fma_f32 v[14:15], v[14:15], v[166:167], v[176:177]
	v_pk_fma_f32 v[12:13], v[12:13], v[164:165], v[174:175]
	global_store_dwordx4 v146, v[12:15], s[22:23] offset:576
	s_waitcnt vmcnt(13)
	v_pk_fma_f32 v[42:43], v[42:43], v[162:163], v[180:181]
	v_pk_fma_f32 v[40:41], v[40:41], v[160:161], v[178:179]
	global_store_dwordx4 v147, v[40:43], s[22:23] offset:512
	s_waitcnt vmcnt(12)
	v_pk_fma_f32 v[10:11], v[10:11], v[166:167], v[184:185]
	v_pk_fma_f32 v[8:9], v[8:9], v[164:165], v[182:183]
	global_store_dwordx4 v147, v[8:11], s[22:23] offset:576
	s_waitcnt vmcnt(11)
	v_pk_fma_f32 v[34:35], v[34:35], v[162:163], v[194:195]
	v_pk_fma_f32 v[32:33], v[32:33], v[160:161], v[192:193]
	global_store_dwordx4 v148, v[32:35], s[22:23] offset:512
	s_waitcnt vmcnt(10)
	v_pk_fma_f32 v[6:7], v[6:7], v[166:167], v[232:233]
	v_pk_fma_f32 v[4:5], v[4:5], v[164:165], v[230:231]
	global_store_dwordx4 v148, v[4:7], s[22:23] offset:576
	s_waitcnt vmcnt(9)
	v_pk_fma_f32 v[30:31], v[30:31], v[162:163], v[236:237]
	v_pk_fma_f32 v[28:29], v[28:29], v[160:161], v[234:235]
	global_store_dwordx4 v149, v[28:31], s[22:23] offset:512
	s_waitcnt vmcnt(8)
	v_pk_fma_f32 v[2:3], v[2:3], v[166:167], v[240:241]
	v_pk_fma_f32 v[0:1], v[0:1], v[164:165], v[238:239]
	global_store_dwordx4 v149, v[0:3], s[22:23] offset:576
	s_mov_b64 s[22:23], -1
	s_cbranch_vccnz .LBB0_1981
	s_andn2_b64 vcc, exec, s[18:19]
	s_cbranch_vccnz .LBB0_1980
	s_barrier
	s_branch .LBB0_1980
